# next item's indexer Q / head-weight loads stay in flight across the selection (raw dwordx2 loads, scale multiply moved to the score prologue)
# speedup vs baseline: 1.1322x; 1.0029x over previous
; DI void sel_load_qw(const Params& p, int item, bf16x8 (&qf)[4], float (&wq)[16], int lane) {
;   const bf16* PE = (const bf16*)(p.ws + WS_PE); const float* IW = (const float*)(p.ws + WS_IW);
;   const int r32 = lane & 31, h = lane >> 5, b = item >> 11, t0 = (item & 2047) * 4; const size_t rowb = (size_t)b * SEQ;
;   load_q(qf, PE + (rowb + t0 + (r32 >> 3)) * NPE + E_IQ + (r32 & 7) * 64, h);
; #pragma unroll
;   for (int q = 0; q < 4; ++q) { const f32x4 w4 = *(const f32x4*)(IW + (rowb + t0 + q) * 8 + 4 * h);
;     wq[4 * q] = w4.x * 0.04419417382415922f; wq[4 * q + 1] = w4.y * 0.04419417382415922f; wq[4 * q + 2] = w4.z * 0.04419417382415922f; wq[4 * q + 3] = w4.w * 0.04419417382415922f; }
; }
; __global__ void __launch_bounds__(NTHREADS) fwd_kernel(Params p) {
;     ...
;     bf16x8 sqf[4]; float swq[16];
;     if (SEL_ITEM(0) < 2 * 2048) sel_load_qw(p, SEL_ITEM(0), sqf, swq, lane);
.LBB0_397:
	s_or_b64 exec, exec, s[0:1]
	v_readlane_b32 s0, v254, 3
	v_readlane_b32 s1, v254, 4
	s_waitcnt lgkmcnt(0)
	s_barrier
	s_load_dwordx2 s[6:7], s[0:1], 0xd0
	s_mov_b32 s1, 0
	v_mov_b32_e32 v0, v182
	s_waitcnt lgkmcnt(0)
	s_add_u32 s4, s6, 0xe200000
	s_addc_u32 s5, s7, 0
	v_writelane_b32 v254, s4, 16
	s_cmpk_lt_i32 s25, 0x1000
	s_nop 0
	v_writelane_b32 v254, s5, 17
	v_writelane_b32 v254, s0, 18
	s_nop 1
	v_writelane_b32 v254, s1, 19
	s_cbranch_scc0 .LBB0_399
	s_ashr_i32 s0, s25, 11
	s_ashr_i32 s1, s0, 31
	s_lshl_b32 s2, s25, 2
	s_lshl_b64 s[0:1], s[0:1], 13
	s_and_b32 s2, s2, 0x1ffc
	s_or_b32 s0, s0, s2
	s_lshl_b64 s[2:3], s[0:1], 5
	v_lshrrev_b32_e32 v1, 3, v0
	s_add_u32 s2, s4, s2
	v_and_or_b32 v1, v1, 3, s0
	s_movk_i32 s0, 0x1800
	v_mov_b64_e32 v[2:3], s[6:7]
	s_addc_u32 s3, s5, s3
	v_mad_u64_u32 v[2:3], s[4:5], v1, s0, v[2:3]
	v_mov_b32_e32 v1, 0x1800
	v_mad_i32_i24 v3, s1, v1, v3
	v_lshlrev_b32_e32 v1, 7, v0
	v_and_b32_e32 v16, 0x380, v1
	v_mov_b32_e32 v17, 0
	v_lshrrev_b32_e32 v0, 1, v0
	v_lshl_add_u64 v[18:19], v[2:3], 0, v[16:17]
	v_and_b32_e32 v16, 16, v0
	global_load_dwordx2 v[112:113], v16, s[2:3] offset:96
	global_load_dwordx2 v[98:99], v16, s[2:3] offset:104
	global_load_dwordx2 v[110:111], v16, s[2:3] offset:64
	global_load_dwordx2 v[100:101], v16, s[2:3] offset:72
	global_load_dwordx2 v[108:109], v16, s[2:3] offset:32
	global_load_dwordx2 v[102:103], v16, s[2:3] offset:40
	global_load_dwordx2 v[106:107], v16, s[2:3]
	global_load_dwordx2 v[104:105], v16, s[2:3] offset:8
	v_lshl_add_u64 v[16:17], v[18:19], 0, v[16:17]
	global_load_dwordx4 v[32:35], v[16:17], off offset:1280
	global_load_dwordx4 v[36:39], v[16:17], off offset:1312
	global_load_dwordx4 v[40:43], v[16:17], off offset:1344
	global_load_dwordx4 v[44:47], v[16:17], off offset:1376
	s_branch .LBB0_400

; DI void sel_load_qw(const Params& p, int item, bf16x8 (&qf)[4], float (&wq)[16], int lane) {
;     ...
;     wq[4 * q] = w4.x * 0.04419417382415922f; wq[4 * q + 1] = w4.y * 0.04419417382415922f; wq[4 * q + 2] = w4.z * 0.04419417382415922f; wq[4 * q + 3] = w4.w * 0.04419417382415922f; }
.Lsc_pre2:
	v_mul_f32_e32 v98, 0x3d3504f3, v98
	v_mul_f32_e32 v99, 0x3d3504f3, v99
	v_mul_f32_e32 v100, 0x3d3504f3, v100
	v_mul_f32_e32 v101, 0x3d3504f3, v101
	v_mul_f32_e32 v102, 0x3d3504f3, v102
	v_mul_f32_e32 v103, 0x3d3504f3, v103
	v_mul_f32_e32 v104, 0x3d3504f3, v104
	v_mul_f32_e32 v105, 0x3d3504f3, v105
	v_mul_f32_e32 v106, 0x3d3504f3, v106
	v_mul_f32_e32 v107, 0x3d3504f3, v107
	v_mul_f32_e32 v108, 0x3d3504f3, v108
	v_mul_f32_e32 v109, 0x3d3504f3, v109
	v_mul_f32_e32 v110, 0x3d3504f3, v110
	v_mul_f32_e32 v111, 0x3d3504f3, v111
	v_mul_f32_e32 v112, 0x3d3504f3, v112
	v_mul_f32_e32 v113, 0x3d3504f3, v113

; DI void sel_load_qw(const Params& p, int item, bf16x8 (&qf)[4], float (&wq)[16], int lane) {
;   const bf16* PE = (const bf16*)(p.ws + WS_PE); const float* IW = (const float*)(p.ws + WS_IW);
;   const int r32 = lane & 31, h = lane >> 5, b = item >> 11, t0 = (item & 2047) * 4; const size_t rowb = (size_t)b * SEQ;
;   load_q(qf, PE + (rowb + t0 + (r32 >> 3)) * NPE + E_IQ + (r32 & 7) * 64, h);
; #pragma unroll
;   for (int q = 0; q < 4; ++q) { const f32x4 w4 = *(const f32x4*)(IW + (rowb + t0 + q) * 8 + 4 * h);
;     wq[4 * q] = w4.x * 0.04419417382415922f; wq[4 * q + 1] = w4.y * 0.04419417382415922f; wq[4 * q + 2] = w4.z * 0.04419417382415922f; wq[4 * q + 3] = w4.w * 0.04419417382415922f; }
; }
; DI void selectA_item(const Params& p, int item, int next_item, char* lds, bf16x8 (&qf)[4], float (&wq)[16]) {
;     ...
;   if (next_item >= 0) sel_load_qw(p, next_item, qf, wq, lane);
.LBB0_415:
	s_or_b64 exec, exec, s[2:3]
	v_readlane_b32 s4, v254, 3
	v_readlane_b32 s5, v254, 4
	s_load_dwordx2 s[2:3], s[4:5], 0x158
	s_and_b64 s[0:1], s[0:1], exec
	v_readlane_b32 s0, v254, 12
	v_readlane_b32 s1, v254, 55
	s_cselect_b32 s0, s15, s0
	s_waitcnt lgkmcnt(0)
	s_mul_i32 s1, s1, s2
	s_add_i32 s0, s0, s1
	s_cmpk_lt_i32 s0, 0x1000
	s_cselect_b32 s0, s0, -1
	s_cmp_lt_i32 s0, 0
	v_writelane_b32 v254, s1, 57
	s_cbranch_scc1 .Lq_nonext
	v_readlane_b32 s2, v254, 18
	v_readlane_b32 s3, v254, 19
	s_lshr_b32 s4, s0, 11
	s_lshl_b32 s0, s0, 2
	s_mov_b32 s1, s3
	s_mov_b32 s5, s3
	s_and_b32 s2, s0, 0x1ffc
	v_writelane_b32 v254, s0, 18
	v_lshrrev_b32_e32 v0, 3, v72
	s_nop 0
	v_writelane_b32 v254, s1, 19
	s_lshl_b64 s[0:1], s[4:5], 13
	s_or_b32 s0, s0, s2
	v_readlane_b32 s2, v254, 45
	v_readlane_b32 s3, v254, 46
	v_and_or_b32 v2, v0, 3, s0
	s_nop 0
	v_mov_b64_e32 v[0:1], s[2:3]
	s_movk_i32 s2, 0x1800
	v_mad_u64_u32 v[0:1], s[2:3], v2, s2, v[0:1]
	v_lshlrev_b32_e32 v2, 7, v67
	v_mad_u32_u24 v1, s1, v185, v1
	v_and_b32_e32 v48, 0x380, v2
	v_readlane_b32 s2, v254, 16
	v_lshl_add_u64 v[20:21], v[0:1], 0, v[48:49]
	v_lshlrev_b32_e32 v48, 4, v71
	v_readlane_b32 s3, v254, 17
	s_lshl_b64 s[0:1], s[0:1], 5
	v_lshl_add_u64 v[20:21], v[20:21], 0, v[48:49]
	v_lshl_add_u64 v[0:1], s[2:3], 0, v[48:49]
	v_lshl_add_u64 v[12:13], v[0:1], 0, s[0:1]
	global_load_dwordx2 v[112:113], v[12:13], off offset:96
	global_load_dwordx2 v[98:99], v[12:13], off offset:104
	global_load_dwordx2 v[110:111], v[12:13], off offset:64
	global_load_dwordx2 v[100:101], v[12:13], off offset:72
	global_load_dwordx2 v[108:109], v[12:13], off offset:32
	global_load_dwordx2 v[102:103], v[12:13], off offset:40
	global_load_dwordx2 v[106:107], v[12:13], off
	global_load_dwordx2 v[104:105], v[12:13], off offset:8
	global_load_dwordx4 v[32:35], v[20:21], off offset:1280
	global_load_dwordx4 v[36:39], v[20:21], off offset:1312
	global_load_dwordx4 v[40:43], v[20:21], off offset:1344
	global_load_dwordx4 v[44:47], v[20:21], off offset:1376
	s_waitcnt vmcnt(12)
	s_branch .LBB0_417

; DI unsigned cvtpk(float lo, float hi) { f32x2_t v = {lo, hi}; bf16x2_t b = __builtin_convertvector(v, bf16x2_t); return __builtin_bit_cast(unsigned, b); }
; DI void lds_barrier() { asm volatile("s_waitcnt lgkmcnt(0)" ::: "memory"); __builtin_amdgcn_s_barrier(); asm volatile("" ::: "memory"); }
; DI float ord2f(unsigned k) { return __uint_as_float((k & 0x80000000u) ? (k ^ 0x80000000u) : ~k); }
; DI void selectA_item(const Params& p, int item, int next_item, char* lds, bf16x8 (&qf)[4], float (&wq)[16]) {
;     ...
;   { u32x2 w; w.x = cvtpk(pcv.x, pcv.y); w.y = cvtpk(pcv.z, pcv.w); ((u32x2*)(p.ws + WS_PBF))[(size_t)item * 512 + tid] = w; }
;   lds_barrier();
;   {
;     const int g = wid >> 1, gt = tid & 127, upper = wid & 1;
;     const int t = t0 + g, n = t + 1;
;     const bool big = n > 256;
;     const float* scq = sc + g * 8192;
;     unsigned short* out = SEL + (rowb + t) * 256;
;     int* histq = hist + g * 1024;
;     unsigned long long* clq = clist + g * 128;
;     int* mq = misc + 32 + g * 8;
;     const float lo = ord2f(mm[g * 2]), hi = ord2f(mm[g * 2 + 1]);
;     const float scale = (hi > lo) ? 1023.f / (hi - lo) : 0.f;
;     for (int i = gt; i < 1024; i += 128) histq[i] = 0;
;     if (gt == 0) { mq[0] = 0; mq[6] = 0; }
;     lds_barrier();
;     float uu[64];
; #pragma unroll
;     for (int i = 0; i < 64; ++i) { const int idx = gt + 128 * i; const float v = (idx < n) ? scq[idx] : lo; const float u = (v - lo) * scale; uu[i] = u;
;       if (big && idx < n) { int bb = (int)u; bb = bb > 1023 ? 1023 : bb; atomicAdd(&histq[bb], 1); } }
.LBB0_417:
	v_readlane_b32 s0, v254, 26
	v_readlane_b32 s1, v254, 27
	v_cvt_pk_bf16_f32 v0, v16, v17
	v_cvt_pk_bf16_f32 v1, v18, v19
	v_lshl_add_u64 v[2:3], v[76:77], 3, s[0:1]
	global_store_dwordx2 v[2:3], v[0:1], off
	v_and_b32_e32 v180, 0x7f, v182
	v_lshrrev_b32_e32 v0, 7, v182
	v_lshlrev_b32_e32 v1, 12, v0
	v_lshl_add_u32 v1, v180, 5, v1
	v_add_u32_e32 v1, 0x20000, v1
	v_mov_b32_e32 v2, 0
	v_mov_b32_e32 v3, 0
	v_mov_b32_e32 v4, 0
	v_mov_b32_e32 v5, 0
	ds_write_b128 v1, v[2:5]
	ds_write_b128 v1, v[2:5] offset:16
	v_lshlrev_b32_e32 v6, 10, v0
	v_lshl_add_u32 v6, v180, 3, v6
	v_add_u32_e32 v6, 0x24180, v6
	ds_write_b64 v6, v[2:3]
	v_lshlrev_b32_e32 v7, 5, v0
	v_add_u32_e32 v7, 0x24080, v7
	v_cmp_eq_u32_e32 vcc, 0, v180
	s_and_saveexec_b64 s[0:1], vcc
	ds_write_b128 v7, v[2:5]
	ds_write_b128 v7, v[2:5] offset:16
	s_or_b64 exec, exec, s[0:1]
	s_waitcnt lgkmcnt(0)
	s_barrier
	s_lshl_b64 s[82:83], s[52:53], 13
	v_lshrrev_b32_e32 v0, 6, v182
	v_mov_b32_e32 v204, 0x80000000
	v_readfirstlane_b32 s36, v0
	v_readlane_b32 s39, v254, 58
	v_readlane_b32 s62, v254, 22
	v_readlane_b32 s63, v254, 23
	v_mov_b32_e32 v205, 0x2404c
	v_mov_b32_e32 v206, 1
	s_lshr_b32 s37, s36, 1
	s_and_b32 s38, s36, 1
	s_add_i32 s40, s39, s37
	s_add_i32 s40, s40, 1
	s_lshl_b32 s41, s37, 12
	s_add_i32 s41, s41, 0x20000
	s_lshl_b32 s42, s37, 5
	s_add_i32 s42, s42, 0x24080
	s_lshl_b32 s43, s37, 10
	s_add_i32 s43, s43, 0x24180
	s_lshl_b32 s0, s52, 13
	s_add_i32 s0, s0, s40
	s_add_i32 s0, s0, -1
	s_lshl_b32 s0, s0, 9
	s_add_u32 s62, s62, s0
	s_addc_u32 s63, s63, 0
	s_lshl_b32 s84, s37, 15
	v_lshl_add_u32 v181, v180, 2, s84
	v_mov_b32_e32 v207, s42
	s_mov_b32 s65, 0
	s_cmp_gt_u32 s40, 0x100
	s_cbranch_scc1 .Lsel_big
	v_cmp_gt_u32_e32 vcc, s40, v180
	s_and_saveexec_b64 s[0:1], vcc
	v_lshlrev_b32_e32 v0, 1, v180
	global_store_short v0, v180, s[62:63]
	s_or_b64 exec, exec, s[0:1]
	v_add_u32_e32 v1, 0x80, v180
	v_cmp_gt_u32_e32 vcc, s40, v1
	s_and_saveexec_b64 s[0:1], vcc
	v_lshlrev_b32_e32 v0, 1, v1
	global_store_short v0, v1, s[62:63]
	s_or_b64 exec, exec, s[0:1]
	s_mov_b32 s65, 1
	s_branch .Lsel_B_done
